# post-phase inner loop: second x-row/param load group hoisted to loop top as global_load with counted vmcnt(4), one global round trip fewer per iteration; on top of v37
# speedup vs baseline: 1.0004x; 1.0004x over previous
; #define LAS __attribute__((address_space(3)))
; __device__ __forceinline__ float shx(float v, int lane, int o) { return __builtin_bit_cast(float, __builtin_amdgcn_ds_bpermute((lane ^ o) << 2, __builtin_bit_cast(int, v))); }
; __device__ __forceinline__ void post_phase(const Args& a, int li, LAS unsigned char* lds) {
;     ...
;           for (int tb = 0; tb < 8; ++tb) {
;               f32x4 G[4];
; #pragma unroll
;               for (int cb = 0; cb < 4; ++cb) G[cb] = (f32x4){0.f, 0.f, 0.f, 0.f};
; #pragma unroll
;               for (int kk = 0; kk < 4; ++kk) { const bf16x8 Bf = *(const LAS bf16x8*)(lds + PZ_SG + (16 * tb + n16) * 272 + (32 * kk + 8 * q4) * 2);
; #pragma unroll
;                   for (int cb = 0; cb < 4; ++cb) G[cb] = __builtin_amdgcn_mfma_f32_16x16x32_bf16(Ag[cb][kk], Bf, G[cb], 0, 0, 0); }
;               const int tl = 16 * tb + n16; const size_t tt = t0 + tl; const bool hasprev = (p0 + tl) > 0;
;               f32x4 y[4]; float s = 0.f;
; #pragma unroll
;               for (int cb = 0; cb < 4; ++cb) { { const u32x2 yw_ = *(const u32x2*)(ys + tt * 512 + 64 * h + 16 * cb + 4 * q4); y[cb] = (f32x4){bflo(yw_.x), bfhi(yw_.x), bflo(yw_.y), bfhi(yw_.y)}; } s += (y[cb].x + y[cb].y) + (y[cb].z + y[cb].w); }
;               s += shx(s, lane, 16); s += shx(s, lane, 32); const float mean = s * (1.f / 64.f); float qq = 0.f;
; #pragma unroll
;               for (int cb = 0; cb < 4; ++cb) { y[cb] = y[cb] - mean; qq += (y[cb].x * y[cb].x + y[cb].y * y[cb].y) + (y[cb].z * y[cb].z + y[cb].w * y[cb].w); }
;               qq += shx(qq, lane, 16); qq += shx(qq, lane, 32); const float rstd = 1.0f / sqrtf(qq * (1.f / 64.f) + 64e-5f);
;               const float bon = bong[tt * 8 + h];
; #pragma unroll
;               for (int cb = 0; cb < 4; ++cb) { const int c = 64 * h + 16 * cb + 4 * q4;
;                   const u32x2 cv = *(const u32x2*)(proj + tt * P_EVEN + 1024 + c); u32x2 pv = {0u, 0u}; if (hasprev) pv = *(const u32x2*)(proj + (tt - 1) * P_EVEN + 1024 + c);
.LBB0_658:
	v_add_u32_e32 v178, s2, v97
	v_add_u32_e32 v64, 0x11400, v178
	ds_read_b128 v[64:67], v64
	v_add_u32_e32 v68, 0x11440, v178
	ds_read_b128 v[68:71], v68
	v_lshl_add_u64 v[166:167], s[24:25], 0, v[160:161]
	s_brev_b32 s0, 52
	s_waitcnt vmcnt(0) lgkmcnt(0)
	v_mfma_f32_16x16x32_bf16 v[72:75], v[0:3], v[64:67], 0
	v_add_co_u32_e32 v166, vcc, s0, v166
	v_add_u32_e32 v172, 0x11480, v178
	v_mfma_f32_16x16x32_bf16 v[76:79], v[16:19], v[64:67], 0
	v_addc_co_u32_e32 v167, vcc, 0, v167, vcc
	global_load_dwordx2 v[170:171], v[166:167], off
	global_load_dwordx2 v[188:189], v[166:167], off offset:64
	global_load_dwordx2 v[202:203], v[166:167], off offset:32
	global_load_dwordx2 v[166:167], v[166:167], off offset:96
	v_lshl_add_u64 v[250:251], s[24:25], 0, v[158:159]
	v_lshl_add_u64 v[204:205], s[24:25], 0, v[150:151]
	v_add_co_u32_e32 v204, vcc, 0xe000000, v204
	s_nop 1
	v_addc_co_u32_e32 v205, vcc, 0, v205, vcc
	global_load_dword v250, v[250:251], off
	global_load_dwordx2 v[204:205], v[204:205], off offset:2048
	v_mfma_f32_16x16x32_bf16 v[162:165], v[32:35], v[64:67], 0
	ds_read_b128 v[192:195], v172
	v_lshl_add_u64 v[190:191], s[24:25], 0, v[150:151]
	s_waitcnt vmcnt(4) lgkmcnt(0)
	v_lshlrev_b32_e32 v196, 16, v188
	v_mfma_f32_16x16x32_bf16 v[64:67], v[48:51], v[64:67], 0
	v_and_b32_e32 v197, 0xffff0000, v188
	v_lshlrev_b32_e32 v198, 16, v189
	v_and_b32_e32 v199, 0xffff0000, v189
	v_mfma_f32_16x16x32_bf16 v[72:75], v[4:7], v[68:71], v[72:75]
	v_add_f32_e32 v188, v196, v197
	v_mfma_f32_16x16x32_bf16 v[76:79], v[20:23], v[68:71], v[76:79]
	v_mfma_f32_16x16x32_bf16 v[162:165], v[36:39], v[68:71], v[162:165]
	v_mfma_f32_16x16x32_bf16 v[68:71], v[52:55], v[68:71], v[64:67]
	s_nop 2
	v_add_u32_e32 v64, 0x114c0, v178
	ds_read_b128 v[64:67], v64
	v_mfma_f32_16x16x32_bf16 v[210:213], v[24:27], v[192:195], v[76:79]
	v_lshlrev_b32_e32 v207, 16, v171
	v_lshlrev_b32_e32 v206, 16, v170
	v_lshl_add_u64 v[76:77], s[24:25], 0, v[158:159]
	v_add_co_u32_e32 v78, vcc, 0xe000000, v190
	v_mfma_f32_16x16x32_bf16 v[242:245], v[40:43], v[192:195], v[162:165]
	s_nop 0
	v_addc_co_u32_e32 v79, vcc, 0, v191, vcc
	s_nop 0
	v_mfma_f32_16x16x32_bf16 v[72:75], v[8:11], v[192:195], v[72:75]
	s_waitcnt vmcnt(0) lgkmcnt(0)
	v_mov_b32_e32 v172, v202
	v_mov_b32_e32 v173, v203
	v_mov_b32_e32 v162, v250
	v_mov_b32_e32 v208, v204
	v_mov_b32_e32 v209, v205
	v_lshlrev_b32_e32 v201, 16, v173
	v_mfma_f32_16x16x32_bf16 v[246:249], v[56:59], v[192:195], v[68:71]
	v_and_b32_e32 v195, 0xffff0000, v171
	v_and_b32_e32 v194, 0xffff0000, v170
	v_lshlrev_b32_e32 v200, 16, v172
	v_and_b32_e32 v203, 0xffff0000, v173
	v_and_b32_e32 v202, 0xffff0000, v172
	v_pk_add_f32 v[68:69], v[206:207], v[194:195]
	v_pk_add_f32 v[70:71], v[200:201], v[202:203]
	v_mfma_f32_16x16x32_bf16 v[76:79], v[12:15], v[64:67], v[72:75]
	v_and_b32_e32 v165, 0xffff0000, v166
	v_lshlrev_b32_e32 v193, 16, v166
	v_lshlrev_b32_e32 v189, 16, v167
	v_add_f32_e32 v72, v68, v69
	v_pk_add_f32 v[68:69], v[70:71], v[70:71] op_sel:[0,1] op_sel_hi:[1,0]
	v_and_b32_e32 v167, 0xffff0000, v167
	v_add_f32_e32 v166, v198, v199
	v_add_f32_e32 v192, 0, v72
	v_mov_b32_e32 v69, v165
	v_pk_add_f32 v[70:71], v[188:189], v[166:167]
	v_pk_add_f32 v[68:69], v[192:193], v[68:69]
	v_mfma_f32_16x16x32_bf16 v[72:75], v[28:31], v[64:67], v[210:213]
	v_add_f32_e64 v68, v68, v70
	v_add_f32_e64 v69, v69, v71
	v_add_u32_e32 v166, s2, v241
	v_add_f32_e32 v68, v68, v69
	ds_bpermute_b32 v69, v89, v68
	v_cmp_ne_u32_e64 s[38:39], 0, v166
	s_waitcnt lgkmcnt(0)
	v_add_f32_e32 v163, v68, v69
	ds_bpermute_b32 v164, v91, v163
	v_mfma_f32_16x16x32_bf16 v[68:71], v[44:47], v[64:67], v[242:245]
	s_waitcnt lgkmcnt(0)
	v_add_f32_e32 v163, v163, v164
	v_fmac_f32_e32 v195, 0xbc800000, v163
	v_fmac_f32_e32 v207, 0xbc800000, v163
	v_fmac_f32_e32 v194, 0xbc800000, v163
	v_fmac_f32_e32 v203, 0xbc800000, v163
	v_fmac_f32_e32 v201, 0xbc800000, v163
	v_fmac_f32_e32 v202, 0xbc800000, v163
	v_fmac_f32_e32 v200, 0xbc800000, v163
	v_fmac_f32_e32 v206, 0xbc800000, v163
	v_mov_b32_e32 v210, v207
	v_mov_b32_e32 v211, v195
	v_mov_b32_e32 v207, v194
	v_mov_b32_e32 v170, v201
	v_mov_b32_e32 v171, v203
	v_mov_b32_e32 v172, v200
	v_mov_b32_e32 v173, v202
	v_fmac_f32_e32 v196, 0xbc800000, v163
	v_pk_mul_f32 v[204:205], v[210:211], v[210:211]
	v_pk_mul_f32 v[212:213], v[206:207], v[206:207]
	v_pk_mul_f32 v[170:171], v[170:171], v[170:171]
	v_pk_mul_f32 v[172:173], v[172:173], v[172:173]
	v_fmac_f32_e32 v198, 0xbc800000, v163
	v_fmac_f32_e32 v197, 0xbc800000, v163
	v_mul_f32_e32 v164, v196, v196
	v_pk_mov_b32 v[244:245], v[212:213], v[204:205] op_sel:[1,0]
	v_mov_b32_e32 v213, v205
	v_pk_mov_b32 v[204:205], v[172:173], v[170:171] op_sel:[1,0]
	v_mov_b32_e32 v173, v171
	v_fmac_f32_e32 v199, 0xbc800000, v163
	v_pk_fma_f32 v[242:243], v[196:197], v[196:197], v[164:165] op_sel_hi:[1,1,0]
	v_pk_add_f32 v[170:171], v[244:245], v[212:213]
	v_pk_add_f32 v[172:173], v[204:205], v[172:173]
	v_mul_f32_e32 v164, v198, v198
	v_pk_add_f32 v[170:171], v[170:171], v[170:171] op_sel_hi:[0,1]
	v_pk_add_f32 v[172:173], v[172:173], v[172:173] op_sel_hi:[0,1]
	v_pk_fma_f32 v[204:205], v[198:199], v[198:199], v[164:165] op_sel_hi:[1,1,0]
	v_fmac_f32_e32 v167, 0xbc800000, v163
	v_fmac_f32_e32 v189, 0xbc800000, v163
	v_fmac_f32_e32 v165, 0xbc800000, v163
	v_fmac_f32_e32 v193, 0xbc800000, v163
	v_mul_f32_e32 v242, v193, v193
	v_mul_f32_e32 v204, v165, v165
	v_mul_f32_e32 v170, v189, v189
	v_mul_f32_e32 v172, v167, v167
	v_pk_add_f32 v[204:205], v[242:243], v[204:205]
	v_pk_add_f32 v[170:171], v[170:171], v[172:173]
	v_mfma_f32_16x16x32_bf16 v[64:67], v[60:63], v[64:67], v[246:249]
	v_add_f32_e64 v170, v204, v170
	v_add_f32_e64 v171, v205, v171
	v_mov_b32_e32 v204, 0
	v_add_f32_e32 v163, v170, v171
	ds_bpermute_b32 v164, v89, v163
	v_mov_b32_e32 v212, 0
	v_mov_b32_e32 v213, 0
	s_waitcnt lgkmcnt(0)
	v_add_f32_e32 v163, v163, v164
	ds_bpermute_b32 v164, v91, v163
	s_and_saveexec_b64 s[0:1], s[38:39]
	s_cbranch_execz .LBB0_660
	v_add_co_u32_e32 v170, vcc, 0xdfff000, v190
	s_nop 1
	v_addc_co_u32_e32 v171, vcc, 0, v191, vcc
	flat_load_dwordx2 v[212:213], v[170:171] offset:512
